# plus DSA attention: K/V tile prefetch into spare VGPRs and interleaved QK MFMA chains with 4 rotating LDS fragment buffers
# speedup vs baseline: 1.0296x; 1.0055x over previous
; template <int DQ, bool MASK>
; DI void attn_phase(const Params& p, unsigned char* smem, float cexp) {
;     ...
;   for (int it = blockIdx.x; it < 1024; it += gridDim.x) {
;     const int seg = it >> 9, idx = it & 511, lv = idx >> 6, bh = idx & 63;
;     const int qb = seg == 0 ? 15 - lv : lv;
;     const int q0 = qb * 128;
;     const int ntile_block = 2 * qb + 2, my_nt = 2 * qb + 1 + (w >> 1);
;     const int b = bh >> 3, h = bh & 7;
;     const size_t tok = (size_t)b * 2048 + q0 + 32 * w + r;
;     bf16x8 qf[DQ / 16];
;     {
;       const bf16* qp = Qb + ((size_t)bh * 2048 + q0 + 32 * w + r) * DQ + 8 * g;
; #pragma unroll
;       for (int s = 0; s < DQ / 16; ++s) qf[s] = *(const bf16x8*)(qp + 16 * s);
;     }
;     f32x16 o[4];
; #pragma unroll
;     for (int j = 0; j < 4; ++j)
; #pragma unroll
;       for (int i = 0; i < 16; ++i) o[j][i] = 0.f;
;     float m = -INFINITY, l = 0.f;
;     ...
;       {
;         constexpr int CPR = DQ / 8;
; #pragma unroll
;         for (int i = 0; i < DQ / 32; ++i) {
;           int c = tid + 256 * i;
;           int row = c / CPR, cc = c % CPR;
;           uint4 v = *(const uint4*)(Kb + ((size_t)bh * 2048 + kt * 64 + row) * DQ + cc * 8);
;           *(uint4*)(Ks + row * KST + cc * 8) = v;
;         }
; #pragma unroll
;         for (int i = 0; i < 4; ++i) {
;           int c = tid + 256 * i;
;           int d = c >> 3, cc = c & 7;
;           uint4 v = *(const uint4*)(Vt + (((size_t)bh * 32 + kt) * 128 + d) * 64 + cc * 8);
;           uint2* dp = (uint2*)(Vs + d * VST + cc * 8);
;           dp[0] = make_uint2(v.x, v.y);
;           dp[1] = make_uint2(v.z, v.w);
;         }
.LBB0_1258:
	s_and_b32 s0, s18, 63
	s_lshl_b32 s1, s18, 8
	s_lshl_b32 s10, s0, 19
	s_bfe_u32 s0, s19, 0x30006
	s_and_b32 s1, s1, 0x3800
	s_and_b32 s20, s19, 63
	s_xor_b32 s6, s0, 15
	s_cmpk_lt_u32 s19, 0x200
	s_cselect_b32 s0, s6, s0
	s_lshl_b32 s21, s0, 7
	s_lshl_b32 s6, s20, 11
	v_lshl_add_u64 v[168:169], v[150:151], 0, s[10:11]
	v_lshl_add_u64 v[170:171], v[152:153], 0, s[10:11]
	v_lshl_add_u64 v[172:173], v[154:155], 0, s[10:11]
	v_lshl_add_u64 v[174:175], v[156:157], 0, s[10:11]
	v_lshl_add_u64 v[176:177], v[158:159], 0, s[10:11]
	v_lshl_add_u64 v[178:179], v[162:163], 0, s[10:11]
	v_lshl_add_u64 v[180:181], v[164:165], 0, s[10:11]
	v_lshl_add_u64 v[182:183], v[166:167], 0, s[10:11]
	s_or_b32 s10, s21, s6
	v_lshl_add_u64 v[2:3], s[10:11], 0, v[144:145]
	v_lshlrev_b64 v[2:3], 8, v[2:3]
	v_lshl_add_u64 v[2:3], v[146:147], 0, v[2:3]
	global_load_dwordx4 v[112:115], v[2:3], off
	global_load_dwordx4 v[116:119], v[2:3], off offset:32
	global_load_dwordx4 v[120:123], v[2:3], off offset:64
	global_load_dwordx4 v[124:127], v[2:3], off offset:96
	global_load_dwordx4 v[128:131], v[2:3], off offset:128
	global_load_dwordx4 v[132:135], v[2:3], off offset:160
	global_load_dwordx4 v[136:139], v[2:3], off offset:192
	global_load_dwordx4 v[140:143], v[2:3], off offset:224
	s_or_b32 s10, s1, s21
	v_lshl_add_u64 v[2:3], v[144:145], 0, s[10:11]
	v_lshlrev_b64 v[2:3], 8, v[2:3]
	v_mov_b32_e32 v14, v0
	v_mov_b32_e32 v15, v0
	s_lshl_b32 s25, s0, 1
	v_lshl_add_u64 v[184:185], v[2:3], 0, s[12:13]
	v_mov_b32_e32 v1, v0
	v_mov_b32_e32 v2, v0
	v_mov_b32_e32 v3, v0
	v_mov_b32_e32 v4, v0
	v_mov_b32_e32 v5, v0
	v_mov_b32_e32 v6, v0
	v_mov_b32_e32 v7, v0
	v_mov_b32_e32 v8, v0
	v_mov_b32_e32 v9, v0
	v_mov_b32_e32 v10, v0
	v_mov_b32_e32 v11, v0
	v_mov_b32_e32 v12, v0
	v_mov_b32_e32 v13, v0
	v_mov_b64_e32 v[30:31], v[14:15]
	v_mov_b64_e32 v[46:47], v[14:15]
	v_mov_b64_e32 v[62:63], v[14:15]
	s_waitcnt vmcnt(9)
	v_mov_b64_e32 v[78:79], v[14:15]
	v_add_u32_e32 v198, s25, v149
	s_add_i32 s25, s25, 2
	v_mov_b64_e32 v[28:29], v[12:13]
	v_mov_b64_e32 v[26:27], v[10:11]
	v_mov_b64_e32 v[24:25], v[8:9]
	v_mov_b64_e32 v[22:23], v[6:7]
	v_mov_b64_e32 v[20:21], v[4:5]
	v_mov_b64_e32 v[18:19], v[2:3]
	v_mov_b64_e32 v[16:17], v[0:1]
	v_mov_b64_e32 v[44:45], v[12:13]
	v_mov_b64_e32 v[42:43], v[10:11]
	v_mov_b64_e32 v[40:41], v[8:9]
	v_mov_b64_e32 v[38:39], v[6:7]
	v_mov_b64_e32 v[36:37], v[4:5]
	v_mov_b64_e32 v[34:35], v[2:3]
	v_mov_b64_e32 v[32:33], v[0:1]
	v_mov_b64_e32 v[60:61], v[12:13]
	v_mov_b64_e32 v[58:59], v[10:11]
	v_mov_b64_e32 v[56:57], v[8:9]
	v_mov_b64_e32 v[54:55], v[6:7]
	v_mov_b64_e32 v[52:53], v[4:5]
	v_mov_b64_e32 v[50:51], v[2:3]
	v_mov_b64_e32 v[48:49], v[0:1]
	v_mov_b64_e32 v[76:77], v[12:13]
	v_mov_b64_e32 v[74:75], v[10:11]
	v_mov_b64_e32 v[72:73], v[8:9]
	v_mov_b64_e32 v[70:71], v[6:7]
	v_mov_b64_e32 v[68:69], v[4:5]
	v_mov_b64_e32 v[66:67], v[2:3]
	v_mov_b64_e32 v[64:65], v[0:1]
	v_mov_b32_e32 v1, 0
	v_mov_b32_e32 v2, 0xff800000
	s_mov_b32 s10, 0
	s_mov_b64 s[68:69], s[22:23]
	s_add_u32 s70, s22, 0xe000000
	s_addc_u32 s71, s23, 0
	s_add_u32 s64, s22, 0x4000
	s_addc_u32 s65, s23, 0
	s_add_u32 s66, s70, 0x4000
	s_addc_u32 s67, s71, 0
	v_lshl_add_u64 v[246:247], s[68:69], 0, v[176:177]
	global_load_dwordx4 v[200:203], v[246:247], off
	v_lshl_add_u64 v[248:249], s[68:69], 0, v[178:179]
	global_load_dwordx4 v[204:207], v[248:249], off
	v_lshl_add_u64 v[246:247], s[68:69], 0, v[180:181]
	global_load_dwordx4 v[208:211], v[246:247], off
	v_lshl_add_u64 v[248:249], s[68:69], 0, v[182:183]
	global_load_dwordx4 v[212:215], v[248:249], off
	v_lshl_add_u64 v[246:247], s[70:71], 0, v[174:175]
	global_load_dwordx4 v[226:229], v[246:247], off
	v_lshl_add_u64 v[248:249], s[70:71], 0, v[172:173]
	global_load_dwordx4 v[230:233], v[248:249], off
	v_lshl_add_u64 v[246:247], s[70:71], 0, v[170:171]
	global_load_dwordx4 v[234:237], v[246:247], off
	v_lshl_add_u64 v[248:249], s[70:71], 0, v[168:169]
	global_load_dwordx4 v[238:241], v[248:249], off
	s_branch .LBB0_1260

; #define MFMA(a, b, c) __builtin_amdgcn_mfma_f32_32x32x16_bf16((a), (b), (c), 0, 0, 0)
; template <int DQ, bool MASK>
; DI void attn_phase(const Params& p, unsigned char* smem, float cexp) {
;     ...
;     for (int kt = 0; kt < ntile_block; ++kt) {
;       __syncthreads();
;       {
;         constexpr int CPR = DQ / 8;
; #pragma unroll
;         for (int i = 0; i < DQ / 32; ++i) {
;           int c = tid + 256 * i;
;           int row = c / CPR, cc = c % CPR;
;           uint4 v = *(const uint4*)(Kb + ((size_t)bh * 2048 + kt * 64 + row) * DQ + cc * 8);
;           *(uint4*)(Ks + row * KST + cc * 8) = v;
;         }
; #pragma unroll
;         for (int i = 0; i < 4; ++i) {
;           int c = tid + 256 * i;
;           int d = c >> 3, cc = c & 7;
;           uint4 v = *(const uint4*)(Vt + (((size_t)bh * 32 + kt) * 128 + d) * 64 + cc * 8);
;           uint2* dp = (uint2*)(Vs + d * VST + cc * 8);
;           dp[0] = make_uint2(v.x, v.y);
;           dp[1] = make_uint2(v.z, v.w);
;         }
;       }
;       __syncthreads();
;       if (kt < my_nt) {
;         f32x16 sa[2];
; #pragma unroll
;         for (int u = 0; u < 2; ++u) {
; #pragma unroll
;           for (int i = 0; i < 16; ++i) sa[u][i] = 0.f;
; #pragma unroll
;           for (int s = 0; s < DQ / 16; ++s) {
;             bf16x8 a = *(const bf16x8*)(Ks + (32 * u + r) * KST + 16 * s + 8 * g);
;             sa[u] = MFMA(a, qf[s], sa[u]);
;           }
;         }
;         if (MASK) {
;           u64 mw = mask[tok * 32 + kt] >> (4 * g);
;           const u32 mlo = (u32)mw, mhi = (u32)(mw >> 32);
; #pragma unroll
;           for (int i = 0; i < 16; ++i) {
;             const u32 bit = 1u << ((i & 3) + 8 * (i >> 2));
;             if (!(mlo & bit)) sa[0][i] = -INFINITY;
;             if (!(mhi & bit)) sa[1][i] = -INFINITY;
;           }
;         }
.LBB0_1260:
	s_barrier
	v_cmp_lt_i32_e32 vcc, s10, v198
	s_waitcnt vmcnt(7)
	ds_write_b128 v187, v[200:203]
	s_waitcnt vmcnt(6)
	ds_write_b128 v188, v[204:207]
	s_waitcnt vmcnt(5)
	ds_write_b128 v189, v[208:211]
	s_waitcnt vmcnt(4)
	ds_write_b128 v190, v[212:215]
	s_waitcnt vmcnt(3)
	ds_write2_b64 v191, v[226:227], v[228:229] offset1:1
	s_waitcnt vmcnt(2)
	ds_write2_b64 v192, v[230:231], v[232:233] offset1:1
	s_waitcnt vmcnt(1)
	ds_write2_b64 v193, v[234:235], v[236:237] offset1:1
	s_waitcnt vmcnt(0)
	ds_write2_b64 v194, v[238:239], v[240:241] offset1:1
	s_waitcnt lgkmcnt(0)
	s_barrier
	v_lshl_add_u64 v[242:243], s[22:23], 0, v[184:185]
	global_load_dwordx2 v[244:245], v[242:243], off
	s_add_i32 s60, s10, 1
	s_cmp_eq_u32 s60, s25
	s_cselect_b64 s[72:73], s[68:69], s[64:65]
	s_cselect_b64 s[74:75], s[70:71], s[66:67]
	v_lshl_add_u64 v[246:247], s[72:73], 0, v[176:177]
	global_load_dwordx4 v[200:203], v[246:247], off
	v_lshl_add_u64 v[248:249], s[72:73], 0, v[178:179]
	global_load_dwordx4 v[204:207], v[248:249], off
	v_lshl_add_u64 v[246:247], s[72:73], 0, v[180:181]
	global_load_dwordx4 v[208:211], v[246:247], off
	v_lshl_add_u64 v[248:249], s[72:73], 0, v[182:183]
	global_load_dwordx4 v[212:215], v[248:249], off
	v_lshl_add_u64 v[246:247], s[74:75], 0, v[174:175]
	global_load_dwordx4 v[226:229], v[246:247], off
	v_lshl_add_u64 v[248:249], s[74:75], 0, v[172:173]
	global_load_dwordx4 v[230:233], v[248:249], off
	v_lshl_add_u64 v[246:247], s[74:75], 0, v[170:171]
	global_load_dwordx4 v[234:237], v[246:247], off
	v_lshl_add_u64 v[248:249], s[74:75], 0, v[168:169]
	global_load_dwordx4 v[238:241], v[248:249], off
	s_and_saveexec_b64 s[16:17], vcc
	s_cbranch_execz .LBB0_1259
	ds_read_b128 v[4:7], v195
	ds_read_b128 v[8:11], v195 offset:8704
	ds_read_b128 v[12:15], v195 offset:32
	ds_read_b128 v[250:253], v195 offset:8736
	s_waitcnt lgkmcnt(3)
	v_mfma_f32_32x32x16_bf16 v[80:95], v[4:7], v[112:115], 0
	ds_read_b128 v[4:7], v195 offset:64
	s_waitcnt lgkmcnt(3)
	v_mfma_f32_32x32x16_bf16 v[96:111], v[8:11], v[112:115], 0
	ds_read_b128 v[8:11], v195 offset:8768
	s_waitcnt lgkmcnt(3)
	v_mfma_f32_32x32x16_bf16 v[80:95], v[12:15], v[116:119], v[80:95]
	ds_read_b128 v[12:15], v195 offset:96
	s_waitcnt lgkmcnt(3)
	v_mfma_f32_32x32x16_bf16 v[96:111], v[250:253], v[116:119], v[96:111]
	ds_read_b128 v[250:253], v195 offset:8800
	s_waitcnt lgkmcnt(3)
	v_mfma_f32_32x32x16_bf16 v[80:95], v[4:7], v[120:123], v[80:95]
	ds_read_b128 v[4:7], v195 offset:128
	s_waitcnt lgkmcnt(3)
	v_mfma_f32_32x32x16_bf16 v[96:111], v[8:11], v[120:123], v[96:111]
	ds_read_b128 v[8:11], v195 offset:8832
	s_waitcnt lgkmcnt(3)
	v_mfma_f32_32x32x16_bf16 v[80:95], v[12:15], v[124:127], v[80:95]
	ds_read_b128 v[12:15], v195 offset:160
	s_waitcnt lgkmcnt(3)
	v_mfma_f32_32x32x16_bf16 v[96:111], v[250:253], v[124:127], v[96:111]
	ds_read_b128 v[250:253], v195 offset:8864
	s_waitcnt lgkmcnt(3)
	v_mfma_f32_32x32x16_bf16 v[80:95], v[4:7], v[128:131], v[80:95]
	ds_read_b128 v[4:7], v195 offset:192
	s_waitcnt lgkmcnt(3)
	v_mfma_f32_32x32x16_bf16 v[96:111], v[8:11], v[128:131], v[96:111]
	ds_read_b128 v[8:11], v195 offset:8896
	s_waitcnt lgkmcnt(3)
	v_mfma_f32_32x32x16_bf16 v[80:95], v[12:15], v[132:135], v[80:95]
	ds_read_b128 v[12:15], v195 offset:224
	s_waitcnt lgkmcnt(3)
	v_mfma_f32_32x32x16_bf16 v[96:111], v[250:253], v[132:135], v[96:111]
	ds_read_b128 v[250:253], v195 offset:8928
	s_waitcnt lgkmcnt(3)
	v_mfma_f32_32x32x16_bf16 v[80:95], v[4:7], v[136:139], v[80:95]
	s_waitcnt lgkmcnt(2)
	v_mfma_f32_32x32x16_bf16 v[96:111], v[8:11], v[136:139], v[96:111]
	s_waitcnt lgkmcnt(1)
	v_mfma_f32_32x32x16_bf16 v[80:95], v[12:15], v[140:143], v[80:95]
	s_waitcnt lgkmcnt(0)
	v_mfma_f32_32x32x16_bf16 v[96:111], v[250:253], v[140:143], v[96:111]
	s_waitcnt vmcnt(8)
	v_mov_b32_e32 v4, v244
	v_mov_b32_e32 v5, v245
	v_lshrrev_b32_e32 v3, v148, v4
	s_nop 7
	s_nop 1
	v_lshrrev_b64 v[12:13], v148, v[4:5]
	v_and_b32_e32 v3, 1, v3
	v_cmp_eq_u32_e32 vcc, 1, v3
	v_and_b32_e32 v3, 1, v13
	s_nop 0
	v_cndmask_b32_e32 v14, v197, v80, vcc
	v_cmp_eq_u32_e32 vcc, 1, v3
	v_and_b32_e32 v3, 2, v12
	s_nop 3
	v_cndmask_b32_e32 v10, v197, v96, vcc
	v_cmp_ne_u32_e32 vcc, 0, v3
	v_and_b32_e32 v3, 2, v13
	s_nop 0
	v_cndmask_b32_e32 v11, v197, v81, vcc
	v_cmp_ne_u32_e32 vcc, 0, v3
	v_and_b32_e32 v3, 4, v12
	s_nop 0
	v_cndmask_b32_e32 v15, v197, v97, vcc
	v_cmp_ne_u32_e32 vcc, 0, v3
	v_and_b32_e32 v3, 4, v13
	s_nop 0
	v_cndmask_b32_e32 v80, v197, v82, vcc
	v_cmp_ne_u32_e32 vcc, 0, v3
	v_and_b32_e32 v3, 8, v12
	s_nop 0
	v_cndmask_b32_e32 v96, v197, v98, vcc
	v_cmp_ne_u32_e32 vcc, 0, v3
	v_and_b32_e32 v3, 8, v13
	s_nop 0
	v_cndmask_b32_e32 v81, v197, v83, vcc
	v_cmp_ne_u32_e32 vcc, 0, v3
	v_and_b32_e32 v3, 0x100, v12
	s_nop 0
	v_cndmask_b32_e32 v97, v197, v99, vcc
	v_cmp_ne_u32_e32 vcc, 0, v3
	v_and_b32_e32 v3, 0x100, v13
	s_nop 0
	v_cndmask_b32_e32 v82, v197, v84, vcc
	v_cmp_ne_u32_e32 vcc, 0, v3
	v_and_b32_e32 v3, 0x200, v12
	s_nop 0
	v_cndmask_b32_e32 v98, v197, v100, vcc
	v_cmp_ne_u32_e32 vcc, 0, v3
	v_and_b32_e32 v3, 0x200, v13
	s_nop 0
	v_cndmask_b32_e32 v83, v197, v85, vcc
	v_cmp_ne_u32_e32 vcc, 0, v3
	v_and_b32_e32 v3, 0x400, v12
	s_nop 0
	v_cndmask_b32_e32 v99, v197, v101, vcc
	v_cmp_ne_u32_e32 vcc, 0, v3
	v_and_b32_e32 v3, 0x400, v13
	s_nop 0
	v_cndmask_b32_e32 v84, v197, v86, vcc
	v_cmp_ne_u32_e32 vcc, 0, v3
	v_and_b32_e32 v3, 0x800, v12
	s_nop 0
	v_cndmask_b32_e32 v100, v197, v102, vcc
	v_cmp_ne_u32_e32 vcc, 0, v3
	v_and_b32_e32 v3, 0x800, v13
	s_nop 0
	v_cndmask_b32_e32 v85, v197, v87, vcc
	v_cmp_ne_u32_e32 vcc, 0, v3
	v_and_b32_e32 v3, 0x10000, v12
	s_nop 0
	v_cndmask_b32_e32 v101, v197, v103, vcc
	v_cmp_ne_u32_e32 vcc, 0, v3
; #define MFMA(a, b, c) __builtin_amdgcn_mfma_f32_32x32x16_bf16((a), (b), (c), 0, 0, 0)
; template <int DQ, bool MASK>
; DI void attn_phase(const Params& p, unsigned char* smem, float cexp) {
;     ...
;         if (MASK) {
;           u64 mw = mask[tok * 32 + kt] >> (4 * g);
;           const u32 mlo = (u32)mw, mhi = (u32)(mw >> 32);
; #pragma unroll
;           for (int i = 0; i < 16; ++i) {
;             const u32 bit = 1u << ((i & 3) + 8 * (i >> 2));
;             if (!(mlo & bit)) sa[0][i] = -INFINITY;
;             if (!(mhi & bit)) sa[1][i] = -INFINITY;
;           }
;         }
;         float mx = -INFINITY;
; #pragma unroll
;         for (int u = 0; u < 2; ++u)
; #pragma unroll
;           for (int i = 0; i < 16; ++i) mx = fmaxf(mx, sa[u][i]);
;         mx = fmaxf(mx, __shfl_xor(mx, 32));
;         float mnew = fmaxf(m, mx);
;         float muse = (mnew == -INFINITY) ? 0.f : mnew;
;         float alpha = __builtin_amdgcn_exp2f((m - muse) * cexp);
;         m = mnew;
;         float ps = 0.f;
; #pragma unroll
;         for (int u = 0; u < 2; ++u)
; #pragma unroll
;           for (int i = 0; i < 16; ++i) {
;             float pv = __builtin_amdgcn_exp2f((sa[u][i] - muse) * cexp);
;             ps += pv;
;             sa[u][i] = pv;
;           }
;         l = l * alpha + ps;
; #pragma unroll
;         for (int j = 0; j < 4; ++j)
; #pragma unroll
;           for (int i = 0; i < 16; ++i) o[j][i] *= alpha;
; #pragma unroll
;         for (int u = 0; u < 2; ++u)
; #pragma unroll
;           for (int s2 = 0; s2 < 2; ++s2) {
;             uint4 pp;
;             pp.x = pack2(sa[u][8 * s2 + 0], sa[u][8 * s2 + 1]);
;             pp.y = pack2(sa[u][8 * s2 + 2], sa[u][8 * s2 + 3]);
;             pp.z = pack2(sa[u][8 * s2 + 4], sa[u][8 * s2 + 5]);
;             pp.w = pack2(sa[u][8 * s2 + 6], sa[u][8 * s2 + 7]);
;             bf16x8 pf = __builtin_bit_cast(bf16x8, pp);
; #pragma unroll
;             for (int dt = 0; dt < 4; ++dt) {
;               const bf16* vp = Vs + (32 * dt + r) * VST + 32 * u + 16 * s2 + 4 * g;
;               s16x4 lo = *(const s16x4*)vp;
;               s16x4 hi = *(const s16x4*)(vp + 8);
;               bf16x8 vf = __builtin_shufflevector(lo, hi, 0, 1, 2, 3, 4, 5, 6, 7);
;               o[dt] = MFMA(vf, pf, o[dt]);
	v_and_b32_e32 v3, 0x10000, v13
	s_nop 0
	v_cndmask_b32_e32 v86, v197, v88, vcc
	v_cmp_ne_u32_e32 vcc, 0, v3
	v_and_b32_e32 v3, 0x20000, v12
	s_nop 0
	v_cndmask_b32_e32 v88, v197, v104, vcc
	v_cmp_ne_u32_e32 vcc, 0, v3
	v_and_b32_e32 v3, 0x20000, v13
	s_nop 0
	v_cndmask_b32_e32 v87, v197, v89, vcc
	v_cmp_ne_u32_e32 vcc, 0, v3
	v_and_b32_e32 v3, 0x40000, v12
	s_nop 0
	v_cndmask_b32_e32 v89, v197, v105, vcc
	v_cmp_ne_u32_e32 vcc, 0, v3
	v_and_b32_e32 v3, 0x40000, v13
	s_nop 0
	v_cndmask_b32_e32 v90, v197, v90, vcc
	v_cmp_ne_u32_e32 vcc, 0, v3
	v_and_b32_e32 v3, 0x80000, v12
	s_nop 0
	v_cndmask_b32_e32 v8, v197, v106, vcc
	v_cmp_ne_u32_e32 vcc, 0, v3
	v_and_b32_e32 v3, 0x80000, v13
	s_nop 0
	v_cndmask_b32_e32 v91, v197, v91, vcc
	v_cmp_ne_u32_e32 vcc, 0, v3
	v_and_b32_e32 v3, 0x1000000, v12
	s_nop 0
	v_cndmask_b32_e32 v9, v197, v107, vcc
	v_cmp_ne_u32_e32 vcc, 0, v3
	v_and_b32_e32 v3, 0x1000000, v13
	s_nop 0
	v_cndmask_b32_e32 v92, v197, v92, vcc
	v_cmp_ne_u32_e32 vcc, 0, v3
	v_and_b32_e32 v3, 0x2000000, v12
	s_nop 0
	v_cndmask_b32_e32 v6, v197, v108, vcc
	v_cmp_ne_u32_e32 vcc, 0, v3
	v_and_b32_e32 v3, 0x2000000, v13
	s_nop 0
	v_cndmask_b32_e32 v93, v197, v93, vcc
	v_cmp_ne_u32_e32 vcc, 0, v3
	v_and_b32_e32 v3, 0x4000000, v12
	s_nop 0
	v_cndmask_b32_e32 v7, v197, v109, vcc
	v_cmp_ne_u32_e32 vcc, 0, v3
	v_and_b32_e32 v3, 0x4000000, v13
	s_nop 0
	v_cndmask_b32_e32 v94, v197, v94, vcc
	v_cmp_ne_u32_e32 vcc, 0, v3
	v_and_b32_e32 v3, 0x8000000, v12
	s_nop 0
	v_cndmask_b32_e32 v4, v197, v110, vcc
	v_cmp_ne_u32_e32 vcc, 0, v3
	v_and_b32_e32 v3, 0x8000000, v13
	v_add_u32_e32 v110, 0x4000, v196
	v_cndmask_b32_e32 v12, v197, v95, vcc
	v_cmp_ne_u32_e32 vcc, 0, v3
	v_max3_f32 v3, v14, s5, v11
	v_max3_f32 v3, v3, v80, v81
	v_max3_f32 v3, v3, v82, v83
	v_max3_f32 v3, v3, v84, v85
	v_max3_f32 v3, v3, v86, v87
	v_max3_f32 v3, v3, v90, v91
	v_max3_f32 v3, v3, v92, v93
	v_max3_f32 v3, v3, v94, v12
	v_max3_f32 v3, v3, v10, v15
	v_max3_f32 v3, v3, v96, v97
	v_max3_f32 v3, v3, v98, v99
	v_max3_f32 v3, v3, v100, v101
	v_max3_f32 v3, v3, v88, v89
	v_max3_f32 v3, v3, v8, v9
	v_cndmask_b32_e32 v5, v197, v111, vcc
	v_max3_f32 v3, v3, v6, v7
	v_max3_f32 v3, v3, v4, v5
	ds_bpermute_b32 v13, v186, v3
	v_add_u32_e32 v111, 0x7000, v196
	s_waitcnt lgkmcnt(0)
	v_max3_f32 v3, v2, v3, v13
	v_cmp_neq_f32_e32 vcc, s5, v3
	s_nop 1
	v_cndmask_b32_e32 v95, 0, v3, vcc
	v_sub_f32_e32 v11, v11, v95
	v_sub_f32_e32 v13, v14, v95
	v_mul_f32_e32 v11, 0x3e0293ee, v11
	v_mul_f32_e32 v13, 0x3e0293ee, v13
	v_exp_f32_e32 v102, v11
	v_sub_f32_e32 v11, v80, v95
	v_exp_f32_e32 v14, v13
	v_mul_f32_e32 v11, 0x3e0293ee, v11
	v_exp_f32_e32 v103, v11
	v_sub_f32_e32 v11, v81, v95
	v_mul_f32_e32 v11, 0x3e0293ee, v11
	v_exp_f32_e32 v81, v11
	v_sub_f32_e32 v11, v82, v95
	v_add_f32_e32 v13, 0, v14
	v_mul_f32_e32 v11, 0x3e0293ee, v11
	v_exp_f32_e32 v82, v11
	v_add_f32_e32 v11, v102, v13
	v_sub_f32_e32 v13, v83, v95
	v_mul_f32_e32 v13, 0x3e0293ee, v13
	v_exp_f32_e32 v83, v13
	v_sub_f32_e32 v13, v84, v95
	v_mul_f32_e32 v13, 0x3e0293ee, v13
	v_exp_f32_e32 v84, v13
	v_sub_f32_e32 v13, v85, v95
	v_mul_f32_e32 v13, 0x3e0293ee, v13
	v_exp_f32_e32 v85, v13
	v_sub_f32_e32 v13, v86, v95
	v_mul_f32_e32 v13, 0x3e0293ee, v13
	v_exp_f32_e32 v104, v13
	v_sub_f32_e32 v13, v87, v95
	v_mul_f32_e32 v13, 0x3e0293ee, v13
	v_add_f32_e32 v11, v103, v11
	v_exp_f32_e32 v105, v13
	v_sub_f32_e32 v13, v90, v95
	v_add_f32_e32 v11, v81, v11
	v_mul_f32_e32 v13, 0x3e0293ee, v13
	v_add_f32_e32 v11, v82, v11
	v_exp_f32_e32 v90, v13
	v_sub_f32_e32 v13, v91, v95
	v_add_f32_e32 v11, v83, v11
	v_mul_f32_e32 v13, 0x3e0293ee, v13
	v_add_f32_e32 v11, v84, v11
	v_exp_f32_e32 v91, v13
	v_sub_f32_e32 v13, v92, v95
	v_add_f32_e32 v11, v85, v11
	v_mul_f32_e32 v13, 0x3e0293ee, v13
	v_add_f32_e32 v11, v104, v11
	v_exp_f32_e32 v92, v13
	v_add_f32_e32 v11, v105, v11
	v_add_f32_e32 v11, v90, v11
	v_add_f32_e32 v11, v91, v11
	v_add_f32_e32 v106, v92, v11
	v_sub_f32_e32 v11, v93, v95
	v_mul_f32_e32 v11, 0x3e0293ee, v11
	v_exp_f32_e32 v93, v11
	v_sub_f32_e32 v11, v94, v95
	v_sub_f32_e32 v10, v10, v95
	v_mul_f32_e32 v11, 0x3e0293ee, v11
	v_mul_f32_e32 v10, 0x3e0293ee, v10
	v_exp_f32_e32 v94, v11
	v_sub_f32_e32 v11, v12, v95
	v_exp_f32_e32 v108, v10
	v_sub_f32_e32 v10, v15, v95
	v_mul_f32_e32 v11, 0x3e0293ee, v11
	v_mul_f32_e32 v10, 0x3e0293ee, v10
	v_exp_f32_e32 v107, v11
	v_exp_f32_e32 v109, v10
	ds_read2_b64 v[10:13], v110 offset0:128 offset1:130
	v_sub_f32_e32 v2, v2, v95
	v_mul_f32_e32 v2, 0x3e0293ee, v2
	v_exp_f32_e32 v2, v2
	v_cvt_pk_bf16_f32 v80, v14, v102
	v_add_u32_e32 v102, 0x5000, v196
	v_cvt_pk_bf16_f32 v81, v103, v81
	v_pk_mul_f32 v[78:79], v[78:79], v[2:3] op_sel_hi:[1,0]
	v_pk_mul_f32 v[76:77], v[76:77], v[2:3] op_sel_hi:[1,0]
	v_pk_mul_f32 v[74:75], v[74:75], v[2:3] op_sel_hi:[1,0]
	v_pk_mul_f32 v[72:73], v[72:73], v[2:3] op_sel_hi:[1,0]
	v_pk_mul_f32 v[70:71], v[70:71], v[2:3] op_sel_hi:[1,0]
	v_pk_mul_f32 v[68:69], v[68:69], v[2:3] op_sel_hi:[1,0]
	v_pk_mul_f32 v[66:67], v[66:67], v[2:3] op_sel_hi:[1,0]
	v_pk_mul_f32 v[64:65], v[64:65], v[2:3] op_sel_hi:[1,0]
	v_cvt_pk_bf16_f32 v82, v82, v83
	v_cvt_pk_bf16_f32 v83, v84, v85
	ds_read2_b64 v[84:87], v102 offset0:160 offset1:162
	v_add_u32_e32 v103, 0x6000, v196
	s_waitcnt lgkmcnt(1)
; #define MFMA(a, b, c) __builtin_amdgcn_mfma_f32_32x32x16_bf16((a), (b), (c), 0, 0, 0)
; template <int DQ, bool MASK>
; DI void attn_phase(const Params& p, unsigned char* smem, float cexp) {
;     ...
; #pragma unroll
;         for (int u = 0; u < 2; ++u)
; #pragma unroll
;           for (int i = 0; i < 16; ++i) {
;             float pv = __builtin_amdgcn_exp2f((sa[u][i] - muse) * cexp);
;             ps += pv;
;             sa[u][i] = pv;
;           }
;         l = l * alpha + ps;
; #pragma unroll
;         for (int j = 0; j < 4; ++j)
; #pragma unroll
;           for (int i = 0; i < 16; ++i) o[j][i] *= alpha;
; #pragma unroll
;         for (int u = 0; u < 2; ++u)
; #pragma unroll
;           for (int s2 = 0; s2 < 2; ++s2) {
;             uint4 pp;
;             pp.x = pack2(sa[u][8 * s2 + 0], sa[u][8 * s2 + 1]);
;             pp.y = pack2(sa[u][8 * s2 + 2], sa[u][8 * s2 + 3]);
;             pp.z = pack2(sa[u][8 * s2 + 4], sa[u][8 * s2 + 5]);
;             pp.w = pack2(sa[u][8 * s2 + 6], sa[u][8 * s2 + 7]);
;             bf16x8 pf = __builtin_bit_cast(bf16x8, pp);
; #pragma unroll
;             for (int dt = 0; dt < 4; ++dt) {
;               const bf16* vp = Vs + (32 * dt + r) * VST + 32 * u + 16 * s2 + 4 * g;
;               s16x4 lo = *(const s16x4*)vp;
;               s16x4 hi = *(const s16x4*)(vp + 8);
;               bf16x8 vf = __builtin_shufflevector(lo, hi, 0, 1, 2, 3, 4, 5, 6, 7);
;               o[dt] = MFMA(vf, pf, o[dt]);
;             }
;           }
;       }
	v_mfma_f32_32x32x16_bf16 v[64:79], v[10:13], v[80:83], v[64:79]
	ds_read2_b64 v[10:13], v103 offset0:192 offset1:194
	v_mul_f32_e64 v62, v62, v2
	v_mul_f32_e64 v63, v63, v2
	v_mul_f32_e64 v60, v60, v2
	v_mul_f32_e64 v61, v61, v2
	v_pk_mul_f32 v[58:59], v[58:59], v[2:3] op_sel_hi:[1,0]
	v_pk_mul_f32 v[56:57], v[56:57], v[2:3] op_sel_hi:[1,0]
	v_pk_mul_f32 v[54:55], v[54:55], v[2:3] op_sel_hi:[1,0]
	v_pk_mul_f32 v[52:53], v[52:53], v[2:3] op_sel_hi:[1,0]
	v_pk_mul_f32 v[50:51], v[50:51], v[2:3] op_sel_hi:[1,0]
	v_pk_mul_f32 v[48:49], v[48:49], v[2:3] op_sel_hi:[1,0]
	v_pk_mul_f32 v[46:47], v[46:47], v[2:3] op_sel_hi:[1,0]
	v_pk_mul_f32 v[44:45], v[44:45], v[2:3] op_sel_hi:[1,0]
	v_pk_mul_f32 v[42:43], v[42:43], v[2:3] op_sel_hi:[1,0]
	v_pk_mul_f32 v[40:41], v[40:41], v[2:3] op_sel_hi:[1,0]
	v_pk_mul_f32 v[38:39], v[38:39], v[2:3] op_sel_hi:[1,0]
	s_waitcnt lgkmcnt(1)
	v_mfma_f32_32x32x16_bf16 v[48:63], v[84:87], v[80:83], v[48:63]
	v_mul_f32_e64 v36, v36, v2
	v_mul_f32_e64 v37, v37, v2
	v_mul_f32_e64 v34, v34, v2
	v_mul_f32_e64 v35, v35, v2
	v_mul_f32_e64 v32, v32, v2
	v_mul_f32_e64 v33, v33, v2
	ds_read2_b64 v[84:87], v111 offset0:224 offset1:226
	v_pk_mul_f32 v[30:31], v[30:31], v[2:3] op_sel_hi:[1,0]
	v_pk_mul_f32 v[28:29], v[28:29], v[2:3] op_sel_hi:[1,0]
	v_pk_mul_f32 v[26:27], v[26:27], v[2:3] op_sel_hi:[1,0]
	s_waitcnt lgkmcnt(1)
	v_mfma_f32_32x32x16_bf16 v[32:47], v[10:13], v[80:83], v[32:47]
	ds_read2_b64 v[10:13], v110 offset0:132 offset1:134
	v_mul_f32_e64 v24, v24, v2
	v_mul_f32_e64 v25, v25, v2
	v_mul_f32_e64 v22, v22, v2
	v_mul_f32_e64 v23, v23, v2
	v_pk_mul_f32 v[20:21], v[20:21], v[2:3] op_sel_hi:[1,0]
	v_pk_mul_f32 v[18:19], v[18:19], v[2:3] op_sel_hi:[1,0]
	v_pk_mul_f32 v[16:17], v[16:17], v[2:3] op_sel_hi:[1,0]
	v_sub_f32_e32 v14, v96, v95
	v_mul_f32_e32 v14, 0x3e0293ee, v14
	s_waitcnt lgkmcnt(1)
	v_mfma_f32_32x32x16_bf16 v[16:31], v[84:87], v[80:83], v[16:31]
	v_cvt_pk_bf16_f32 v80, v104, v105
	v_cvt_pk_bf16_f32 v81, v90, v91
	v_cvt_pk_bf16_f32 v82, v92, v93
	v_cvt_pk_bf16_f32 v83, v94, v107
	ds_read2_b64 v[84:87], v102 offset0:164 offset1:166
	v_exp_f32_e32 v90, v14
	v_sub_f32_e32 v8, v8, v95
	s_waitcnt lgkmcnt(1)
	v_mfma_f32_32x32x16_bf16 v[64:79], v[10:13], v[80:83], v[64:79]
	v_sub_f32_e32 v10, v97, v95
	v_mul_f32_e32 v10, 0x3e0293ee, v10
	v_exp_f32_e32 v91, v10
	v_sub_f32_e32 v10, v98, v95
	v_mul_f32_e32 v14, 0x3e0293ee, v10
	ds_read2_b64 v[10:13], v103 offset0:196 offset1:198
	v_exp_f32_e32 v92, v14
	s_waitcnt lgkmcnt(1)
	v_mfma_f32_32x32x16_bf16 v[48:63], v[84:87], v[80:83], v[48:63]
	v_sub_f32_e32 v14, v99, v95
	ds_read2_b64 v[84:87], v111 offset0:228 offset1:230
	v_mul_f32_e32 v14, 0x3e0293ee, v14
	v_exp_f32_e32 v96, v14
	v_sub_f32_e32 v14, v100, v95
	v_mul_f32_e32 v14, 0x3e0293ee, v14
	v_exp_f32_e32 v97, v14
	s_waitcnt lgkmcnt(1)
	v_mfma_f32_32x32x16_bf16 v[32:47], v[10:13], v[80:83], v[32:47]
	v_sub_f32_e32 v10, v101, v95
	v_mul_f32_e32 v10, 0x3e0293ee, v10
	v_exp_f32_e32 v98, v10
	v_sub_f32_e32 v10, v88, v95
	v_mul_f32_e32 v14, 0x3e0293ee, v10
	ds_read2_b64 v[10:13], v110 offset0:136 offset1:138
	v_exp_f32_e32 v88, v14
	s_waitcnt lgkmcnt(1)
	v_mfma_f32_32x32x16_bf16 v[16:31], v[84:87], v[80:83], v[16:31]
	ds_read2_b64 v[84:87], v102 offset0:168 offset1:170
	v_sub_f32_e32 v14, v89, v95
	v_cvt_pk_bf16_f32 v80, v108, v109
	v_cvt_pk_bf16_f32 v81, v90, v91
	v_cvt_pk_bf16_f32 v82, v92, v96
	v_cvt_pk_bf16_f32 v83, v97, v98
	v_mul_f32_e32 v8, 0x3e0293ee, v8
	v_exp_f32_e32 v99, v8
	s_waitcnt lgkmcnt(1)
	v_mfma_f32_32x32x16_bf16 v[64:79], v[10:13], v[80:83], v[64:79]
	v_mul_f32_e32 v10, 0x3e0293ee, v14
	v_exp_f32_e32 v89, v10
	v_sub_f32_e32 v12, v9, v95
	ds_read2_b64 v[8:11], v103 offset0:200 offset1:202
	v_mul_f32_e32 v12, 0x3e0293ee, v12
	v_sub_f32_e32 v6, v6, v95
	v_mul_f32_e32 v6, 0x3e0293ee, v6
	s_waitcnt lgkmcnt(1)
	v_mfma_f32_32x32x16_bf16 v[48:63], v[84:87], v[80:83], v[48:63]
	v_exp_f32_e32 v84, v12
	ds_read2_b64 v[12:15], v111 offset0:232 offset1:234
	v_exp_f32_e32 v85, v6
	v_sub_f32_e32 v6, v7, v95
	v_sub_f32_e32 v4, v4, v95
	v_mul_f32_e32 v6, 0x3e0293ee, v6
	v_mul_f32_e32 v4, 0x3e0293ee, v4
	s_waitcnt lgkmcnt(1)
	v_mfma_f32_32x32x16_bf16 v[32:47], v[8:11], v[80:83], v[32:47]
	v_exp_f32_e32 v86, v6
	v_exp_f32_e32 v87, v4
	v_sub_f32_e32 v8, v5, v95
	ds_read2_b64 v[4:7], v110 offset0:140 offset1:142
	v_mul_f32_e32 v8, 0x3e0293ee, v8
	v_cvt_pk_bf16_f32 v9, v99, v84
	v_cvt_pk_bf16_f32 v10, v85, v86
	s_waitcnt lgkmcnt(1)
	v_mfma_f32_32x32x16_bf16 v[16:31], v[12:15], v[80:83], v[16:31]
	v_exp_f32_e32 v80, v8
	ds_read2_b64 v[12:15], v102 offset0:172 offset1:174
	v_cvt_pk_bf16_f32 v8, v88, v89
	v_cvt_pk_bf16_f32 v11, v87, v80
	s_waitcnt lgkmcnt(1)
	s_nop 0
	v_mfma_f32_32x32x16_bf16 v[64:79], v[4:7], v[8:11], v[64:79]
	v_add_f32_e32 v4, v93, v106
	v_add_f32_e32 v4, v94, v4
	v_add_f32_e32 v4, v107, v4
	v_add_f32_e32 v4, v108, v4
	v_add_f32_e32 v4, v109, v4
	v_add_f32_e32 v81, v90, v4
	ds_read2_b64 v[4:7], v103 offset0:204 offset1:206
	s_waitcnt lgkmcnt(1)
	v_mfma_f32_32x32x16_bf16 v[48:63], v[12:15], v[8:11], v[48:63]
	v_add_f32_e32 v12, v91, v81
	v_add_f32_e32 v12, v92, v12
	v_add_f32_e32 v12, v96, v12
	v_add_f32_e32 v12, v97, v12
	v_add_f32_e32 v12, v98, v12
	v_add_f32_e32 v81, v88, v12
	ds_read2_b64 v[12:15], v111 offset0:236 offset1:238
	s_waitcnt lgkmcnt(1)
	v_mfma_f32_32x32x16_bf16 v[32:47], v[4:7], v[8:11], v[32:47]
	v_add_f32_e32 v4, v89, v81
	v_add_f32_e32 v4, v99, v4
	v_add_f32_e32 v4, v84, v4
	v_add_f32_e32 v4, v85, v4
	v_add_f32_e32 v4, v86, v4
	v_add_f32_e32 v4, v87, v4
	v_add_f32_e32 v4, v80, v4
	s_waitcnt lgkmcnt(0)
	v_mfma_f32_32x32x16_bf16 v[16:31], v[12:15], v[8:11], v[16:31]
	v_fmac_f32_e32 v4, v1, v2
	v_mov_b32_e32 v1, v4
	v_mov_b32_e32 v2, v3
	s_branch .LBB0_1259
